# HGRN c3 readout: the four gate-tile loads issued together at readout start (three were issued singly and waited on immediately)
# speedup vs baseline: 1.0079x; 1.0016x over previous
; DEV unsigned pack2(float a, float b) { f32x2 v = {a, b}; return __builtin_bit_cast(unsigned, __builtin_convertvector(v, bf2_t)); }
; DEV float bflo(unsigned u) { return __uint_as_float(u << 16); }
; DEV float bfhi(unsigned u) { return __uint_as_float(u & 0xffff0000u); }
; DEV float sigm(float x) { return 1.f / (1.f + __expf(-x)); }
; DEV void phase_hg_c3(const Params& p, char* smem) {
;     ...
; #pragma unroll
;     for (int i = 0; i < 2; i++)
; #pragma unroll
;       for (int j = 0; j < 4; j++)
; #pragma unroll
;         for (int r = 0; r < 4; r++) Ob[(wm * 32 + i * 16 + quad * 4 + r) * 132 + wn * 64 + j * 16 + l15] = acc[i][j][r];
;     __syncthreads();
;     {
;       const int t = tid >> 2, q4 = tid & 3;
;       float vals[32]; float ss = 0.f;
; #pragma unroll
;       for (int j = 0; j < 4; j++) {
;         const int dv = (j * 4 + q4) * 8;
;         float4 a = *(const float4*)(Ob + t * 132 + dv), bq = *(const float4*)(Ob + t * 132 + dv + 4);
;         vals[j * 8 + 0] = a.x; vals[j * 8 + 1] = a.y; vals[j * 8 + 2] = a.z; vals[j * 8 + 3] = a.w;
;         vals[j * 8 + 4] = bq.x; vals[j * 8 + 5] = bq.y; vals[j * 8 + 6] = bq.z; vals[j * 8 + 7] = bq.w;
;       }
; #pragma unroll
;       for (int i = 0; i < 32; i++) ss += vals[i] * vals[i];
;       ss += __shfl_xor(ss, 1); ss += __shfl_xor(ss, 2);
;       const float rinv = rsqrtf(ss * (1.f / 128.f) + 1e-6f);
;       const float* ng = p.in[I_HGNG];
; #pragma unroll
;       for (int j = 0; j < 4; j++) {
;         const int col = h * 128 + (j * 4 + q4) * 8;
;         uint4 gu = *(const uint4*)(GH + (size_t)(r0 + t) * 1024 + col);
;         float4 na = *(const float4*)(ng + col), nb = *(const float4*)(ng + col + 4);
;         float g0 = bflo(gu.x), g1 = bfhi(gu.x), g2 = bflo(gu.y), g3 = bfhi(gu.y), g4 = bflo(gu.z), g5 = bfhi(gu.z), g6 = bflo(gu.w), g7 = bfhi(gu.w);
;         uint4 o;
;         o.x = pack2(vals[j * 8 + 0] * rinv * na.x * g0 * sigm(g0), vals[j * 8 + 1] * rinv * na.y * g1 * sigm(g1));
;         o.y = pack2(vals[j * 8 + 2] * rinv * na.z * g2 * sigm(g2), vals[j * 8 + 3] * rinv * na.w * g3 * sigm(g3));
;         o.z = pack2(vals[j * 8 + 4] * rinv * nb.x * g4 * sigm(g4), vals[j * 8 + 5] * rinv * nb.y * g5 * sigm(g5));
;         o.w = pack2(vals[j * 8 + 6] * rinv * nb.z * g6 * sigm(g6), vals[j * 8 + 7] * rinv * nb.w * g7 * sigm(g7));
.LBB0_276:
	v_add_u32_e32 v0, 0x400, v155
	s_barrier
	ds_write2_b32 v155, v2, v6 offset1:16
	ds_write2_b32 v155, v3, v7 offset0:132 offset1:148
	ds_write2_b32 v0, v4, v8 offset0:8 offset1:24
	ds_write2_b32 v0, v5, v9 offset0:140 offset1:156
	ds_write2_b32 v155, v10, v14 offset0:32 offset1:48
	ds_write2_b32 v155, v11, v15 offset0:164 offset1:180
	ds_write2_b32 v0, v12, v16 offset0:40 offset1:56
	ds_write2_b32 v0, v13, v17 offset0:172 offset1:188
	v_add_u32_e32 v0, 0x2000, v155
	v_add_u32_e32 v2, 0x2400, v155
	ds_write2_b32 v0, v18, v22 offset0:64 offset1:80
	ds_write2_b32 v0, v19, v23 offset0:196 offset1:212
	ds_write2_b32 v2, v20, v24 offset0:72 offset1:88
	ds_write2_b32 v2, v21, v25 offset0:204 offset1:220
	ds_write2_b32 v0, v26, v30 offset0:96 offset1:112
	ds_write2_b32 v0, v27, v31 offset0:228 offset1:244
	ds_write2_b32 v2, v28, v32 offset0:104 offset1:120
	ds_write2_b32 v2, v29, v33 offset0:236 offset1:252
	v_mbcnt_hi_u32_b32 v0, -1, v215
	v_and_b32_e32 v7, 64, v0
	v_xor_b32_e32 v6, 1, v0
	v_add_u32_e32 v7, 64, v7
	v_cmp_lt_i32_e32 vcc, v6, v7
	v_readlane_b32 s6, v255, 11
	s_waitcnt lgkmcnt(0)
	v_cndmask_b32_e32 v6, v0, v6, vcc
	v_lshlrev_b32_e32 v159, 2, v6
	v_xor_b32_e32 v6, 2, v0
	v_cmp_lt_i32_e32 vcc, v6, v7
	v_or_b32_e32 v12, s6, v130
	v_readlane_b32 s6, v254, 60
	v_cndmask_b32_e32 v0, v0, v6, vcc
	v_add_u32_e32 v6, s95, v125
	v_ashrrev_i32_e32 v7, 31, v6
	v_lshlrev_b64 v[8:9], 11, v[6:7]
	v_readlane_b32 s7, v254, 61
	v_lshlrev_b32_e32 v158, 2, v0
	v_lshlrev_b32_e32 v0, 1, v12
	v_lshl_add_u64 v[8:9], s[6:7], 0, v[8:9]
	v_readlane_b32 s6, v254, 62
	v_readlane_b32 s7, v254, 63
	v_lshl_add_u64 v[44:45], v[8:9], 0, v[0:1]
	s_barrier
	v_mov_b64_e32 v[10:11], s[6:7]
	s_movk_i32 s6, 0x880
	v_mad_i64_i32 v[10:11], s[6:7], v6, s6, v[10:11]
	global_load_dwordx4 v[6:9], v[44:45], off
	global_load_dwordx4 v[172:175], v[44:45], off offset:64
	global_load_dwordx4 v[176:179], v[44:45], off offset:128
	global_load_dwordx4 v[180:183], v[44:45], off offset:192
	v_lshlrev_b32_e32 v157, 2, v12
	v_readlane_b32 s14, v253, 51
	v_readlane_b32 s15, v253, 52
	ds_read_b128 v[2:5], v156 offset:400
	ds_read_b128 v[34:37], v156
	ds_read_b128 v[26:29], v156 offset:16
	s_nop 1
	global_load_dwordx4 v[30:33], v157, s[14:15] offset:16
	global_load_dwordx4 v[38:41], v157, s[14:15]
	v_lshl_add_u64 v[42:43], v[10:11], 0, v[0:1]
	ds_read_b128 v[18:21], v156 offset:144
	ds_read_b128 v[22:25], v156 offset:128
	s_waitcnt lgkmcnt(3)
	v_pk_mul_f32 v[106:107], v[34:35], v[34:35]
	v_pk_mul_f32 v[104:105], v[36:37], v[36:37]
	s_waitcnt lgkmcnt(2)
	v_pk_mul_f32 v[100:101], v[26:27], v[26:27]
	v_pk_mul_f32 v[98:99], v[28:29], v[28:29]
	s_waitcnt lgkmcnt(0)
	v_pk_mul_f32 v[114:115], v[22:23], v[22:23]
	v_pk_mul_f32 v[112:113], v[24:25], v[24:25]
	v_pk_mul_f32 v[110:111], v[18:19], v[18:19]
	v_pk_mul_f32 v[108:109], v[20:21], v[20:21]
	v_pk_mul_f32 v[60:61], v[2:3], v[2:3]
	v_pk_mul_f32 v[58:59], v[4:5], v[4:5]
	v_readlane_b32 s20, v254, 51
	v_readlane_b32 s22, v254, 53
	v_readlane_b32 s20, v255, 10
	s_add_i32 s20, s20, s22
	s_cmpk_gt_i32 s20, 0x7ff
	v_readlane_b32 s21, v254, 52
	v_readlane_b32 s23, v254, 54
	s_waitcnt vmcnt(5)
	v_lshlrev_b32_e32 v86, 16, v8
	v_and_b32_e32 v87, 0xffff0000, v8
	v_lshlrev_b32_e32 v90, 16, v6
	v_and_b32_e32 v91, 0xffff0000, v6
	v_lshlrev_b32_e32 v88, 16, v7
	v_and_b32_e32 v89, 0xffff0000, v7
	v_mul_f32_e32 v6, 0xbfb8aa3b, v86
	v_mul_f32_e32 v7, 0xbfb8aa3b, v87
	v_exp_f32_e32 v6, v6
	v_exp_f32_e32 v7, v7
	v_lshlrev_b32_e32 v84, 16, v9
	v_and_b32_e32 v85, 0xffff0000, v9
	v_pk_add_f32 v[6:7], v[6:7], 1.0 op_sel_hi:[1,0]
	s_nop 0
	v_div_scale_f32 v8, s[6:7], v7, v7, 1.0
	v_rcp_f32_e32 v9, v8
	s_nop 0
	v_fma_f32 v12, -v8, v9, 1.0
	v_fmac_f32_e32 v9, v12, v9
	v_div_scale_f32 v12, vcc, 1.0, v7, 1.0
	v_mul_f32_e32 v13, v12, v9
	v_fma_f32 v14, -v8, v13, v12
	v_fmac_f32_e32 v13, v14, v9
	v_fma_f32 v8, -v8, v13, v12
	v_div_fmas_f32 v8, v8, v9, v13
	v_div_fixup_f32 v93, v8, v7, 1.0
	v_div_scale_f32 v7, s[6:7], v6, v6, 1.0
	v_rcp_f32_e32 v8, v7
	s_nop 0
	v_fma_f32 v9, -v7, v8, 1.0
	v_fmac_f32_e32 v8, v9, v8
	v_div_scale_f32 v9, vcc, 1.0, v6, 1.0
	v_mul_f32_e32 v12, v9, v8
	v_fma_f32 v13, -v7, v12, v9
	v_fmac_f32_e32 v12, v13, v8
	v_fma_f32 v7, -v7, v12, v9
	v_div_fmas_f32 v7, v7, v8, v12
	v_div_fixup_f32 v92, v7, v6, 1.0
	v_mul_f32_e32 v6, 0xbfb8aa3b, v88
	v_mul_f32_e32 v7, 0xbfb8aa3b, v89
	v_exp_f32_e32 v6, v6
	v_exp_f32_e32 v7, v7
	s_nop 0
	v_pk_add_f32 v[6:7], v[6:7], 1.0 op_sel_hi:[1,0]
	s_nop 0
	v_div_scale_f32 v8, s[6:7], v7, v7, 1.0
	v_rcp_f32_e32 v9, v8
	s_nop 0
	v_fma_f32 v12, -v8, v9, 1.0
	v_fmac_f32_e32 v9, v12, v9
	v_div_scale_f32 v12, vcc, 1.0, v7, 1.0
	v_mul_f32_e32 v13, v12, v9
	v_fma_f32 v14, -v8, v13, v12
	v_fmac_f32_e32 v13, v14, v9
	v_fma_f32 v8, -v8, v13, v12
	v_div_fmas_f32 v8, v8, v9, v13
	v_div_fixup_f32 v95, v8, v7, 1.0
	v_div_scale_f32 v7, s[6:7], v6, v6, 1.0
	v_rcp_f32_e32 v8, v7
	s_nop 0
	v_fma_f32 v9, -v7, v8, 1.0
	v_fmac_f32_e32 v8, v9, v8
	v_div_scale_f32 v9, vcc, 1.0, v6, 1.0
	v_mul_f32_e32 v12, v9, v8
	v_fma_f32 v13, -v7, v12, v9
	v_fmac_f32_e32 v12, v13, v8
	v_fma_f32 v7, -v7, v12, v9
	v_div_fmas_f32 v7, v7, v8, v12
	v_div_fixup_f32 v94, v7, v6, 1.0
	v_mul_f32_e32 v6, 0xbfb8aa3b, v90
	v_mul_f32_e32 v7, 0xbfb8aa3b, v91
	v_exp_f32_e32 v6, v6
	v_exp_f32_e32 v7, v7
	s_nop 0
	v_pk_add_f32 v[6:7], v[6:7], 1.0 op_sel_hi:[1,0]
	s_nop 0
	v_div_scale_f32 v8, s[6:7], v7, v7, 1.0
	v_rcp_f32_e32 v9, v8
	s_nop 0
	v_fma_f32 v12, -v8, v9, 1.0
	v_fmac_f32_e32 v9, v12, v9
	v_div_scale_f32 v12, vcc, 1.0, v7, 1.0
	v_mul_f32_e32 v13, v12, v9
	v_fma_f32 v14, -v8, v13, v12
	v_fmac_f32_e32 v13, v14, v9
	v_fma_f32 v8, -v8, v13, v12
	v_div_fmas_f32 v8, v8, v9, v13
	v_div_fixup_f32 v97, v8, v7, 1.0
	v_div_scale_f32 v7, s[6:7], v6, v6, 1.0
	v_rcp_f32_e32 v8, v7
	s_nop 0
	v_fma_f32 v9, -v7, v8, 1.0
	v_fmac_f32_e32 v8, v9, v8
	v_div_scale_f32 v9, vcc, 1.0, v6, 1.0
	v_mul_f32_e32 v12, v9, v8
	v_fma_f32 v13, -v7, v12, v9
	v_fmac_f32_e32 v12, v13, v8
	v_fma_f32 v7, -v7, v12, v9
	v_div_fmas_f32 v7, v7, v8, v12
	v_div_fixup_f32 v96, v7, v6, 1.0
	v_mul_f32_e32 v6, 0xbfb8aa3b, v84
	v_mul_f32_e32 v7, 0xbfb8aa3b, v85
	v_exp_f32_e32 v6, v6
	v_exp_f32_e32 v7, v7
	s_nop 0
	v_pk_add_f32 v[6:7], v[6:7], 1.0 op_sel_hi:[1,0]
	s_nop 0
	v_div_scale_f32 v8, s[6:7], v7, v7, 1.0
	v_rcp_f32_e32 v9, v8
	s_nop 0
	v_fma_f32 v12, -v8, v9, 1.0
	v_fmac_f32_e32 v9, v12, v9
	v_div_scale_f32 v12, vcc, 1.0, v7, 1.0
	v_mul_f32_e32 v13, v12, v9
	v_fma_f32 v14, -v8, v13, v12
	v_fmac_f32_e32 v13, v14, v9
	v_fma_f32 v8, -v8, v13, v12
	v_div_fmas_f32 v8, v8, v9, v13
	v_div_fixup_f32 v103, v8, v7, 1.0
	v_div_scale_f32 v7, s[6:7], v6, v6, 1.0
	v_rcp_f32_e32 v8, v7
	ds_read_b128 v[14:17], v156 offset:256
	v_fma_f32 v9, -v7, v8, 1.0
	v_fmac_f32_e32 v8, v9, v8
	v_div_scale_f32 v9, vcc, 1.0, v6, 1.0
	v_mul_f32_e32 v12, v9, v8
	v_fma_f32 v13, -v7, v12, v9
	v_fmac_f32_e32 v12, v13, v8
	v_fma_f32 v7, -v7, v12, v9
	v_div_fmas_f32 v7, v7, v8, v12
	v_div_fixup_f32 v102, v7, v6, 1.0
	s_waitcnt lgkmcnt(0)
; DEV unsigned pack2(float a, float b) { f32x2 v = {a, b}; return __builtin_bit_cast(unsigned, __builtin_convertvector(v, bf2_t)); }
; DEV float bflo(unsigned u) { return __uint_as_float(u << 16); }
; DEV float bfhi(unsigned u) { return __uint_as_float(u & 0xffff0000u); }
; DEV float sigm(float x) { return 1.f / (1.f + __expf(-x)); }
; DEV void phase_hg_c3(const Params& p, char* smem) {
;     ...
;       float vals[32]; float ss = 0.f;
; #pragma unroll
;       for (int j = 0; j < 4; j++) {
;         const int dv = (j * 4 + q4) * 8;
;         float4 a = *(const float4*)(Ob + t * 132 + dv), bq = *(const float4*)(Ob + t * 132 + dv + 4);
;         vals[j * 8 + 0] = a.x; vals[j * 8 + 1] = a.y; vals[j * 8 + 2] = a.z; vals[j * 8 + 3] = a.w;
;         vals[j * 8 + 4] = bq.x; vals[j * 8 + 5] = bq.y; vals[j * 8 + 6] = bq.z; vals[j * 8 + 7] = bq.w;
;       }
; #pragma unroll
;       for (int i = 0; i < 32; i++) ss += vals[i] * vals[i];
;       ss += __shfl_xor(ss, 1); ss += __shfl_xor(ss, 2);
;       const float rinv = rsqrtf(ss * (1.f / 128.f) + 1e-6f);
;       const float* ng = p.in[I_HGNG];
; #pragma unroll
;       for (int j = 0; j < 4; j++) {
;         const int col = h * 128 + (j * 4 + q4) * 8;
;         uint4 gu = *(const uint4*)(GH + (size_t)(r0 + t) * 1024 + col);
;         float4 na = *(const float4*)(ng + col), nb = *(const float4*)(ng + col + 4);
;         float g0 = bflo(gu.x), g1 = bfhi(gu.x), g2 = bflo(gu.y), g3 = bfhi(gu.y), g4 = bflo(gu.z), g5 = bfhi(gu.z), g6 = bflo(gu.w), g7 = bfhi(gu.w);
;         uint4 o;
;         o.x = pack2(vals[j * 8 + 0] * rinv * na.x * g0 * sigm(g0), vals[j * 8 + 1] * rinv * na.y * g1 * sigm(g1));
	v_pk_mul_f32 v[122:123], v[14:15], v[14:15]
	v_pk_mul_f32 v[120:121], v[16:17], v[16:17]
	s_waitcnt vmcnt(0)
	v_mov_b32_e32 v6, v172
	v_mov_b32_e32 v7, v173
	v_mov_b32_e32 v8, v174
	v_mov_b32_e32 v9, v175
	v_lshlrev_b32_e32 v48, 16, v8
	v_and_b32_e32 v49, 0xffff0000, v8
	v_mul_f32_e32 v0, 0xbfb8aa3b, v48
	v_lshlrev_b32_e32 v52, 16, v6
	v_and_b32_e32 v53, 0xffff0000, v6
	v_exp_f32_e32 v6, v0
	v_mul_f32_e32 v0, 0xbfb8aa3b, v49
	v_lshlrev_b32_e32 v50, 16, v7
	v_and_b32_e32 v51, 0xffff0000, v7
	v_exp_f32_e32 v7, v0
	v_lshlrev_b32_e32 v46, 16, v9
	v_and_b32_e32 v47, 0xffff0000, v9
	v_pk_add_f32 v[6:7], v[6:7], 1.0 op_sel_hi:[1,0]
	s_nop 0
	v_div_scale_f32 v0, s[6:7], v7, v7, 1.0
	v_rcp_f32_e32 v8, v0
	s_nop 0
	v_fma_f32 v9, -v0, v8, 1.0
	v_fmac_f32_e32 v8, v9, v8
	v_div_scale_f32 v9, vcc, 1.0, v7, 1.0
	v_mul_f32_e32 v10, v9, v8
	v_fma_f32 v11, -v0, v10, v9
	v_fmac_f32_e32 v10, v11, v8
	v_fma_f32 v0, -v0, v10, v9
	v_div_fmas_f32 v0, v0, v8, v10
	v_div_fixup_f32 v55, v0, v7, 1.0
	v_div_scale_f32 v0, s[6:7], v6, v6, 1.0
	v_rcp_f32_e32 v7, v0
	s_nop 0
	v_fma_f32 v8, -v0, v7, 1.0
	v_fmac_f32_e32 v7, v8, v7
	v_div_scale_f32 v8, vcc, 1.0, v6, 1.0
	v_mul_f32_e32 v9, v8, v7
	v_fma_f32 v10, -v0, v9, v8
	v_fmac_f32_e32 v9, v10, v7
	v_fma_f32 v0, -v0, v9, v8
	v_div_fmas_f32 v0, v0, v7, v9
	v_div_fixup_f32 v54, v0, v6, 1.0
	v_mul_f32_e32 v0, 0xbfb8aa3b, v50
	v_exp_f32_e32 v6, v0
	v_mul_f32_e32 v0, 0xbfb8aa3b, v51
	v_exp_f32_e32 v7, v0
	s_nop 0
	v_pk_add_f32 v[6:7], v[6:7], 1.0 op_sel_hi:[1,0]
	s_nop 0
	v_div_scale_f32 v0, s[6:7], v7, v7, 1.0
	v_rcp_f32_e32 v8, v0
	s_nop 0
	v_fma_f32 v9, -v0, v8, 1.0
	v_fmac_f32_e32 v8, v9, v8
	v_div_scale_f32 v9, vcc, 1.0, v7, 1.0
	v_mul_f32_e32 v10, v9, v8
	v_fma_f32 v11, -v0, v10, v9
	v_fmac_f32_e32 v10, v11, v8
	v_fma_f32 v0, -v0, v10, v9
	v_div_fmas_f32 v0, v0, v8, v10
	v_div_fixup_f32 v57, v0, v7, 1.0
	v_div_scale_f32 v0, s[6:7], v6, v6, 1.0
	v_rcp_f32_e32 v7, v0
	s_nop 0
	v_fma_f32 v8, -v0, v7, 1.0
	v_fmac_f32_e32 v7, v8, v7
	v_div_scale_f32 v8, vcc, 1.0, v6, 1.0
	v_mul_f32_e32 v9, v8, v7
	v_fma_f32 v10, -v0, v9, v8
	v_fmac_f32_e32 v9, v10, v7
	v_fma_f32 v0, -v0, v9, v8
	v_div_fmas_f32 v0, v0, v7, v9
	v_div_fixup_f32 v56, v0, v6, 1.0
	v_mul_f32_e32 v0, 0xbfb8aa3b, v52
	v_exp_f32_e32 v6, v0
	v_mul_f32_e32 v0, 0xbfb8aa3b, v53
	v_exp_f32_e32 v7, v0
	s_nop 0
	v_pk_add_f32 v[6:7], v[6:7], 1.0 op_sel_hi:[1,0]
	s_nop 0
	v_div_scale_f32 v0, s[6:7], v7, v7, 1.0
	v_rcp_f32_e32 v8, v0
	s_nop 0
	v_fma_f32 v9, -v0, v8, 1.0
	v_fmac_f32_e32 v8, v9, v8
	v_div_scale_f32 v9, vcc, 1.0, v7, 1.0
	v_mul_f32_e32 v10, v9, v8
	v_fma_f32 v11, -v0, v10, v9
	v_fmac_f32_e32 v10, v11, v8
	v_fma_f32 v0, -v0, v10, v9
	v_div_fmas_f32 v0, v0, v8, v10
	v_div_fixup_f32 v63, v0, v7, 1.0
	v_div_scale_f32 v0, s[6:7], v6, v6, 1.0
	v_rcp_f32_e32 v7, v0
	s_nop 0
	v_fma_f32 v8, -v0, v7, 1.0
	v_fmac_f32_e32 v7, v8, v7
	v_div_scale_f32 v8, vcc, 1.0, v6, 1.0
	v_mul_f32_e32 v9, v8, v7
	v_fma_f32 v10, -v0, v9, v8
	v_fmac_f32_e32 v9, v10, v7
	v_fma_f32 v0, -v0, v9, v8
	v_div_fmas_f32 v0, v0, v7, v9
	v_div_fixup_f32 v62, v0, v6, 1.0
	v_mul_f32_e32 v0, 0xbfb8aa3b, v46
	v_exp_f32_e32 v6, v0
	v_mul_f32_e32 v0, 0xbfb8aa3b, v47
	v_exp_f32_e32 v7, v0
	s_nop 0
	v_pk_add_f32 v[6:7], v[6:7], 1.0 op_sel_hi:[1,0]
	s_nop 0
	v_div_scale_f32 v0, s[6:7], v7, v7, 1.0
	v_rcp_f32_e32 v8, v0
	s_nop 0
	v_fma_f32 v9, -v0, v8, 1.0
	v_fmac_f32_e32 v8, v9, v8
	v_div_scale_f32 v9, vcc, 1.0, v7, 1.0
	v_mul_f32_e32 v10, v9, v8
	v_fma_f32 v11, -v0, v10, v9
	v_fmac_f32_e32 v10, v11, v8
	v_fma_f32 v0, -v0, v10, v9
	v_div_fmas_f32 v0, v0, v8, v10
	v_div_fixup_f32 v65, v0, v7, 1.0
	v_div_scale_f32 v0, s[6:7], v6, v6, 1.0
	v_rcp_f32_e32 v7, v0
	s_mov_b32 s6, 0x800000
	v_fma_f32 v8, -v0, v7, 1.0
	v_fmac_f32_e32 v7, v8, v7
	v_div_scale_f32 v8, vcc, 1.0, v6, 1.0
	v_mul_f32_e32 v9, v8, v7
	v_fma_f32 v10, -v0, v9, v8
	v_fmac_f32_e32 v9, v10, v7
	v_fma_f32 v0, -v0, v9, v8
	v_div_fmas_f32 v0, v0, v7, v9
	v_div_fixup_f32 v64, v0, v6, 1.0
	v_add_f32_e32 v0, v106, v107
	v_add_f32_e32 v0, v0, v104
	v_add_f32_e32 v0, v0, v105
	v_add_f32_e32 v0, v0, v100
	v_add_f32_e32 v0, v0, v101
	v_add_f32_e32 v0, v0, v98
	v_add_f32_e32 v0, v0, v99
	v_add_f32_e32 v0, v0, v114
	v_add_f32_e32 v0, v0, v115
	ds_read_b128 v[6:9], v156 offset:272
	v_add_f32_e32 v0, v0, v112
	v_add_f32_e32 v0, v0, v113
	v_add_f32_e32 v0, v0, v110
	v_add_f32_e32 v0, v0, v111
	v_add_f32_e32 v0, v0, v108
	v_add_f32_e32 v0, v0, v109
	v_add_f32_e32 v0, v0, v122
	v_add_f32_e32 v0, v0, v123
	ds_read_b128 v[10:13], v156 offset:384
	v_add_f32_e32 v0, v0, v120
	s_waitcnt lgkmcnt(1)
	v_pk_mul_f32 v[118:119], v[6:7], v[6:7]
	v_add_f32_e32 v0, v0, v121
	v_add_f32_e32 v0, v0, v118
	v_pk_mul_f32 v[116:117], v[8:9], v[8:9]
	v_add_f32_e32 v0, v0, v119
	v_add_f32_e32 v0, v0, v116
	s_waitcnt lgkmcnt(0)
	v_pk_mul_f32 v[162:163], v[10:11], v[10:11]
	v_add_f32_e32 v0, v0, v117
	v_add_f32_e32 v0, v0, v162
	v_pk_mul_f32 v[160:161], v[12:13], v[12:13]
	v_add_f32_e32 v0, v0, v163
	v_add_f32_e32 v0, v0, v160
	v_add_f32_e32 v0, v0, v161
	v_add_f32_e32 v0, v0, v60
	v_add_f32_e32 v0, v0, v61
	v_add_f32_e32 v0, v0, v58
	v_add_f32_e32 v0, v0, v59
	ds_bpermute_b32 v58, v159, v0
	s_waitcnt lgkmcnt(0)
	v_add_f32_e32 v0, v0, v58
	ds_bpermute_b32 v58, v158, v0
	s_waitcnt lgkmcnt(0)
; DEV unsigned pack2(float a, float b) { f32x2 v = {a, b}; return __builtin_bit_cast(unsigned, __builtin_convertvector(v, bf2_t)); }
; DEV float bflo(unsigned u) { return __uint_as_float(u << 16); }
; DEV float bfhi(unsigned u) { return __uint_as_float(u & 0xffff0000u); }
; DEV float sigm(float x) { return 1.f / (1.f + __expf(-x)); }
; DEV void phase_hg_c3(const Params& p, char* smem) {
;     ...
;       const float rinv = rsqrtf(ss * (1.f / 128.f) + 1e-6f);
;       const float* ng = p.in[I_HGNG];
; #pragma unroll
;       for (int j = 0; j < 4; j++) {
;         const int col = h * 128 + (j * 4 + q4) * 8;
;         uint4 gu = *(const uint4*)(GH + (size_t)(r0 + t) * 1024 + col);
;         float4 na = *(const float4*)(ng + col), nb = *(const float4*)(ng + col + 4);
;         float g0 = bflo(gu.x), g1 = bfhi(gu.x), g2 = bflo(gu.y), g3 = bfhi(gu.y), g4 = bflo(gu.z), g5 = bfhi(gu.z), g6 = bflo(gu.w), g7 = bfhi(gu.w);
;         uint4 o;
;         o.x = pack2(vals[j * 8 + 0] * rinv * na.x * g0 * sigm(g0), vals[j * 8 + 1] * rinv * na.y * g1 * sigm(g1));
;         o.y = pack2(vals[j * 8 + 2] * rinv * na.z * g2 * sigm(g2), vals[j * 8 + 3] * rinv * na.w * g3 * sigm(g3));
;         o.z = pack2(vals[j * 8 + 4] * rinv * nb.x * g4 * sigm(g4), vals[j * 8 + 5] * rinv * nb.y * g5 * sigm(g5));
;         o.w = pack2(vals[j * 8 + 6] * rinv * nb.z * g6 * sigm(g6), vals[j * 8 + 7] * rinv * nb.w * g7 * sigm(g7));
;         *(uint4*)(Rout + (size_t)(r0 + t) * LDH + col) = o;
	v_add_f32_e32 v0, v0, v58
	v_fmamk_f32 v0, v0, 0x3c000000, v211
	v_cmp_gt_f32_e32 vcc, s6, v0
	v_mul_f32_e32 v58, 0x4b800000, v0
	s_nop 0
	v_cndmask_b32_e32 v0, v0, v58, vcc
	v_rsq_f32_e32 v0, v0
	s_nop 0
	v_mul_f32_e32 v58, 0x45800000, v0
	v_cndmask_b32_e32 v0, v0, v58, vcc
	v_pk_mul_f32 v[34:35], v[34:35], v[0:1] op_sel_hi:[1,0]
	v_pk_mul_f32 v[36:37], v[36:37], v[0:1] op_sel_hi:[1,0]
	v_pk_mul_f32 v[26:27], v[26:27], v[0:1] op_sel_hi:[1,0]
	v_pk_mul_f32 v[34:35], v[38:39], v[34:35]
	v_pk_mul_f32 v[36:37], v[40:41], v[36:37]
	v_pk_mul_f32 v[26:27], v[30:31], v[26:27]
	v_pk_mul_f32 v[34:35], v[34:35], v[90:91]
	v_pk_mul_f32 v[36:37], v[36:37], v[88:89]
	v_pk_mul_f32 v[26:27], v[26:27], v[86:87]
	v_pk_mul_f32 v[34:35], v[96:97], v[34:35]
	v_pk_mul_f32 v[36:37], v[94:95], v[36:37]
	v_pk_mul_f32 v[26:27], v[92:93], v[26:27]
	v_cvt_pk_bf16_f32 v34, v34, v35
	v_cvt_pk_bf16_f32 v35, v36, v37
	v_cvt_pk_bf16_f32 v36, v26, v27
	v_pk_mul_f32 v[26:27], v[28:29], v[0:1] op_sel_hi:[1,0]
	v_pk_mul_f32 v[22:23], v[22:23], v[0:1] op_sel_hi:[1,0]
	v_pk_mul_f32 v[26:27], v[26:27], v[32:33]
	v_pk_mul_f32 v[24:25], v[24:25], v[0:1] op_sel_hi:[1,0]
	v_pk_mul_f32 v[26:27], v[26:27], v[84:85]
	v_pk_mul_f32 v[18:19], v[18:19], v[0:1] op_sel_hi:[1,0]
	v_pk_mul_f32 v[26:27], v[102:103], v[26:27]
	v_pk_mul_f32 v[14:15], v[14:15], v[0:1] op_sel_hi:[1,0]
	v_cvt_pk_bf16_f32 v37, v26, v27
	global_store_dwordx4 v[42:43], v[34:37], off
	global_load_dwordx4 v[26:29], v157, s[14:15] offset:144
	global_load_dwordx4 v[30:33], v157, s[14:15] offset:128
	v_pk_mul_f32 v[16:17], v[16:17], v[0:1] op_sel_hi:[1,0]
	v_pk_mul_f32 v[6:7], v[6:7], v[0:1] op_sel_hi:[1,0]
	v_pk_mul_f32 v[8:9], v[8:9], v[0:1] op_sel_hi:[1,0]
	v_pk_mul_f32 v[10:11], v[10:11], v[0:1] op_sel_hi:[1,0]
	v_pk_mul_f32 v[12:13], v[12:13], v[0:1] op_sel_hi:[1,0]
	v_pk_mul_f32 v[2:3], v[2:3], v[0:1] op_sel_hi:[1,0]
	v_pk_mul_f32 v[4:5], v[4:5], v[0:1] op_sel_hi:[1,0]
	s_waitcnt vmcnt(1)
	v_pk_mul_f32 v[18:19], v[18:19], v[26:27]
	s_waitcnt vmcnt(0)
	v_pk_mul_f32 v[22:23], v[22:23], v[30:31]
	v_pk_mul_f32 v[24:25], v[24:25], v[32:33]
	v_pk_mul_f32 v[22:23], v[22:23], v[52:53]
	v_pk_mul_f32 v[24:25], v[24:25], v[50:51]
	v_pk_mul_f32 v[18:19], v[18:19], v[48:49]
	v_pk_mul_f32 v[22:23], v[22:23], v[62:63]
	v_pk_mul_f32 v[24:25], v[56:57], v[24:25]
	v_pk_mul_f32 v[18:19], v[54:55], v[18:19]
	v_cvt_pk_bf16_f32 v22, v22, v23
	v_cvt_pk_bf16_f32 v23, v24, v25
	v_cvt_pk_bf16_f32 v24, v18, v19
	v_pk_mul_f32 v[18:19], v[20:21], v[0:1] op_sel_hi:[1,0]
	s_nop 0
	v_pk_mul_f32 v[18:19], v[18:19], v[28:29]
	s_nop 0
	v_pk_mul_f32 v[18:19], v[18:19], v[46:47]
	s_nop 0
	v_pk_mul_f32 v[18:19], v[64:65], v[18:19]
	s_nop 0
	v_cvt_pk_bf16_f32 v25, v18, v19
	global_store_dwordx4 v[42:43], v[22:25], off offset:64
	v_mov_b32_e32 v18, v176
	v_mov_b32_e32 v19, v177
	v_mov_b32_e32 v20, v178
	v_mov_b32_e32 v21, v179
	s_nop 0
	global_load_dwordx4 v[22:25], v157, s[14:15] offset:272
	global_load_dwordx4 v[26:29], v157, s[14:15] offset:256
	s_waitcnt vmcnt(2)
	v_lshlrev_b32_e32 v30, 16, v18
	v_and_b32_e32 v31, 0xffff0000, v18
	v_mul_f32_e32 v34, 0xbfb8aa3b, v30
	s_waitcnt vmcnt(0)
	v_pk_mul_f32 v[14:15], v[14:15], v[26:27]
	v_mul_f32_e32 v26, 0xbfb8aa3b, v31
	v_exp_f32_e32 v34, v34
	v_exp_f32_e32 v35, v26
	v_pk_mul_f32 v[14:15], v[14:15], v[30:31]
	v_lshlrev_b32_e32 v18, 16, v19
	v_and_b32_e32 v19, 0xffff0000, v19
	v_pk_add_f32 v[26:27], v[34:35], 1.0 op_sel_hi:[1,0]
	v_pk_mul_f32 v[16:17], v[16:17], v[28:29]
	v_div_scale_f32 v30, s[6:7], v27, v27, 1.0
	v_rcp_f32_e32 v31, v30
	v_pk_mul_f32 v[16:17], v[16:17], v[18:19]
	v_lshlrev_b32_e32 v32, 16, v20
	v_and_b32_e32 v33, 0xffff0000, v20
	v_fma_f32 v34, -v30, v31, 1.0
	v_fmac_f32_e32 v31, v34, v31
	v_div_scale_f32 v34, vcc, 1.0, v27, 1.0
	v_mul_f32_e32 v35, v34, v31
	v_fma_f32 v36, -v30, v35, v34
	v_fmac_f32_e32 v35, v36, v31
	v_fma_f32 v30, -v30, v35, v34
	v_div_fmas_f32 v30, v30, v31, v35
	v_div_fixup_f32 v27, v30, v27, 1.0
	v_div_scale_f32 v30, s[6:7], v26, v26, 1.0
	v_rcp_f32_e32 v31, v30
	v_pk_mul_f32 v[6:7], v[6:7], v[22:23]
	v_lshlrev_b32_e32 v20, 16, v21
	v_pk_mul_f32 v[6:7], v[6:7], v[32:33]
	v_fma_f32 v34, -v30, v31, 1.0
	v_fmac_f32_e32 v31, v34, v31
	v_div_scale_f32 v34, vcc, 1.0, v26, 1.0
	v_mul_f32_e32 v35, v34, v31
	v_fma_f32 v36, -v30, v35, v34
	v_fmac_f32_e32 v35, v36, v31
	v_fma_f32 v30, -v30, v35, v34
	v_div_fmas_f32 v30, v30, v31, v35
	v_div_fixup_f32 v26, v30, v26, 1.0
	v_pk_mul_f32 v[14:15], v[14:15], v[26:27]
	v_and_b32_e32 v21, 0xffff0000, v21
	v_cvt_pk_bf16_f32 v14, v14, v15
	v_mul_f32_e32 v15, 0xbfb8aa3b, v18
	v_exp_f32_e32 v26, v15
	v_mul_f32_e32 v15, 0xbfb8aa3b, v19
	v_exp_f32_e32 v27, v15
	v_pk_mul_f32 v[8:9], v[8:9], v[24:25]
	v_pk_add_f32 v[18:19], v[26:27], 1.0 op_sel_hi:[1,0]
	s_nop 0
	v_div_scale_f32 v15, s[6:7], v19, v19, 1.0
	v_rcp_f32_e32 v26, v15
	v_pk_mul_f32 v[8:9], v[8:9], v[20:21]
	v_fma_f32 v27, -v15, v26, 1.0
	v_fmac_f32_e32 v26, v27, v26
	v_div_scale_f32 v27, vcc, 1.0, v19, 1.0
	v_mul_f32_e32 v28, v27, v26
	v_fma_f32 v29, -v15, v28, v27
	v_fmac_f32_e32 v28, v29, v26
	v_fma_f32 v15, -v15, v28, v27
	v_div_fmas_f32 v15, v15, v26, v28
	v_div_fixup_f32 v19, v15, v19, 1.0
	v_div_scale_f32 v15, s[6:7], v18, v18, 1.0
	v_rcp_f32_e32 v26, v15
	s_nop 0
	v_fma_f32 v27, -v15, v26, 1.0
	v_fmac_f32_e32 v26, v27, v26
	v_div_scale_f32 v27, vcc, 1.0, v18, 1.0
	v_mul_f32_e32 v28, v27, v26
	v_fma_f32 v29, -v15, v28, v27
	v_fmac_f32_e32 v28, v29, v26
	v_fma_f32 v15, -v15, v28, v27
	v_div_fmas_f32 v15, v15, v26, v28
	v_div_fixup_f32 v18, v15, v18, 1.0
	v_pk_mul_f32 v[16:17], v[18:19], v[16:17]
	s_nop 0
	v_cvt_pk_bf16_f32 v15, v16, v17
	v_mul_f32_e32 v16, 0xbfb8aa3b, v32
; DEV unsigned pack2(float a, float b) { f32x2 v = {a, b}; return __builtin_bit_cast(unsigned, __builtin_convertvector(v, bf2_t)); }
; DEV float bflo(unsigned u) { return __uint_as_float(u << 16); }
; DEV float bfhi(unsigned u) { return __uint_as_float(u & 0xffff0000u); }
; DEV float sigm(float x) { return 1.f / (1.f + __expf(-x)); }
; DEV void phase_hg_c3(const Params& p, char* smem) {
;     ...
;       for (int j = 0; j < 4; j++) {
;         const int col = h * 128 + (j * 4 + q4) * 8;
;         uint4 gu = *(const uint4*)(GH + (size_t)(r0 + t) * 1024 + col);
;         float4 na = *(const float4*)(ng + col), nb = *(const float4*)(ng + col + 4);
;         float g0 = bflo(gu.x), g1 = bfhi(gu.x), g2 = bflo(gu.y), g3 = bfhi(gu.y), g4 = bflo(gu.z), g5 = bfhi(gu.z), g6 = bflo(gu.w), g7 = bfhi(gu.w);
;         uint4 o;
;         o.x = pack2(vals[j * 8 + 0] * rinv * na.x * g0 * sigm(g0), vals[j * 8 + 1] * rinv * na.y * g1 * sigm(g1));
;         o.y = pack2(vals[j * 8 + 2] * rinv * na.z * g2 * sigm(g2), vals[j * 8 + 3] * rinv * na.w * g3 * sigm(g3));
;         o.z = pack2(vals[j * 8 + 4] * rinv * nb.x * g4 * sigm(g4), vals[j * 8 + 5] * rinv * nb.y * g5 * sigm(g5));
;         o.w = pack2(vals[j * 8 + 6] * rinv * nb.z * g6 * sigm(g6), vals[j * 8 + 7] * rinv * nb.w * g7 * sigm(g7));
;         *(uint4*)(Rout + (size_t)(r0 + t) * LDH + col) = o;
;       }
	v_mul_f32_e32 v17, 0xbfb8aa3b, v33
	v_exp_f32_e32 v16, v16
	v_exp_f32_e32 v17, v17
	s_nop 0
	v_pk_add_f32 v[16:17], v[16:17], 1.0 op_sel_hi:[1,0]
	s_nop 0
	v_div_scale_f32 v18, s[6:7], v17, v17, 1.0
	v_rcp_f32_e32 v19, v18
	s_nop 0
	v_fma_f32 v22, -v18, v19, 1.0
	v_fmac_f32_e32 v19, v22, v19
	v_div_scale_f32 v22, vcc, 1.0, v17, 1.0
	v_mul_f32_e32 v23, v22, v19
	v_fma_f32 v26, -v18, v23, v22
	v_fmac_f32_e32 v23, v26, v19
	v_fma_f32 v18, -v18, v23, v22
	v_div_fmas_f32 v18, v18, v19, v23
	v_div_fixup_f32 v17, v18, v17, 1.0
	v_div_scale_f32 v18, s[6:7], v16, v16, 1.0
	v_rcp_f32_e32 v19, v18
	s_nop 0
	v_fma_f32 v22, -v18, v19, 1.0
	v_fmac_f32_e32 v19, v22, v19
	v_div_scale_f32 v22, vcc, 1.0, v16, 1.0
	v_mul_f32_e32 v23, v22, v19
	v_fma_f32 v26, -v18, v23, v22
	v_fmac_f32_e32 v23, v26, v19
	v_fma_f32 v18, -v18, v23, v22
	v_div_fmas_f32 v18, v18, v19, v23
	v_div_fixup_f32 v16, v18, v16, 1.0
	v_pk_mul_f32 v[6:7], v[16:17], v[6:7]
	s_nop 0
	v_cvt_pk_bf16_f32 v16, v6, v7
	v_mul_f32_e32 v6, 0xbfb8aa3b, v20
	v_mul_f32_e32 v7, 0xbfb8aa3b, v21
	v_exp_f32_e32 v6, v6
	v_exp_f32_e32 v7, v7
	s_nop 0
	v_pk_add_f32 v[6:7], v[6:7], 1.0 op_sel_hi:[1,0]
	s_nop 0
	v_div_scale_f32 v17, s[6:7], v7, v7, 1.0
	v_rcp_f32_e32 v18, v17
	s_nop 0
	v_fma_f32 v19, -v17, v18, 1.0
	v_fmac_f32_e32 v18, v19, v18
	v_div_scale_f32 v19, vcc, 1.0, v7, 1.0
	v_mul_f32_e32 v20, v19, v18
	v_fma_f32 v21, -v17, v20, v19
	v_fmac_f32_e32 v20, v21, v18
	v_fma_f32 v17, -v17, v20, v19
	v_div_fmas_f32 v17, v17, v18, v20
	v_div_fixup_f32 v7, v17, v7, 1.0
	v_div_scale_f32 v17, s[6:7], v6, v6, 1.0
	v_rcp_f32_e32 v18, v17
	s_nop 0
	v_fma_f32 v19, -v17, v18, 1.0
	v_fmac_f32_e32 v18, v19, v18
	v_div_scale_f32 v19, vcc, 1.0, v6, 1.0
	v_mul_f32_e32 v20, v19, v18
	v_fma_f32 v21, -v17, v20, v19
	v_fmac_f32_e32 v20, v21, v18
	v_fma_f32 v17, -v17, v20, v19
	v_div_fmas_f32 v17, v17, v18, v20
	v_div_fixup_f32 v6, v17, v6, 1.0
	v_pk_mul_f32 v[6:7], v[6:7], v[8:9]
	s_nop 0
	v_cvt_pk_bf16_f32 v17, v6, v7
	global_store_dwordx4 v[42:43], v[14:17], off offset:128
	s_nop 1
	v_mov_b32_e32 v14, v180
	v_mov_b32_e32 v15, v181
	v_mov_b32_e32 v16, v182
	v_mov_b32_e32 v17, v183
	s_nop 0
	global_load_dwordx4 v[6:9], v157, s[14:15] offset:400
	global_load_dwordx4 v[20:23], v157, s[14:15] offset:384
	s_waitcnt vmcnt(2)
	v_lshlrev_b32_e32 v24, 16, v14
	v_and_b32_e32 v25, 0xffff0000, v14
	v_lshlrev_b32_e32 v26, 16, v15
	v_and_b32_e32 v27, 0xffff0000, v15
	v_lshlrev_b32_e32 v18, 16, v16
	v_and_b32_e32 v19, 0xffff0000, v16
	v_lshlrev_b32_e32 v14, 16, v17
	v_and_b32_e32 v15, 0xffff0000, v17
	v_mul_f32_e32 v16, 0xbfb8aa3b, v24
	v_mul_f32_e32 v17, 0xbfb8aa3b, v25
	v_exp_f32_e32 v16, v16
	v_exp_f32_e32 v17, v17
	s_waitcnt vmcnt(0)
	v_pk_mul_f32 v[10:11], v[10:11], v[20:21]
	v_pk_mul_f32 v[12:13], v[12:13], v[22:23]
	v_pk_mul_f32 v[10:11], v[10:11], v[24:25]
	v_pk_add_f32 v[16:17], v[16:17], 1.0 op_sel_hi:[1,0]
	v_pk_mul_f32 v[12:13], v[12:13], v[26:27]
	v_div_scale_f32 v20, s[6:7], v17, v17, 1.0
	v_rcp_f32_e32 v21, v20
	v_pk_mul_f32 v[2:3], v[2:3], v[6:7]
	v_mul_f32_e32 v6, 0xbfb8aa3b, v19
	v_pk_mul_f32 v[2:3], v[2:3], v[18:19]
	v_fma_f32 v24, -v20, v21, 1.0
	v_fmac_f32_e32 v21, v24, v21
	v_div_scale_f32 v24, vcc, 1.0, v17, 1.0
	v_mul_f32_e32 v25, v24, v21
	v_fma_f32 v28, -v20, v25, v24
	v_fmac_f32_e32 v25, v28, v21
	v_fma_f32 v20, -v20, v25, v24
	v_div_fmas_f32 v20, v20, v21, v25
	v_div_fixup_f32 v17, v20, v17, 1.0
	v_div_scale_f32 v20, s[6:7], v16, v16, 1.0
	v_rcp_f32_e32 v21, v20
	v_mul_f32_e32 v0, 0xbfb8aa3b, v15
	v_pk_mul_f32 v[4:5], v[4:5], v[8:9]
	v_fma_f32 v24, -v20, v21, 1.0
	v_fmac_f32_e32 v21, v24, v21
	v_div_scale_f32 v24, vcc, 1.0, v16, 1.0
	v_mul_f32_e32 v25, v24, v21
	v_fma_f32 v28, -v20, v25, v24
	v_fmac_f32_e32 v25, v28, v21
	v_fma_f32 v20, -v20, v25, v24
	v_div_fmas_f32 v20, v20, v21, v25
	v_div_fixup_f32 v16, v20, v16, 1.0
	v_pk_mul_f32 v[10:11], v[10:11], v[16:17]
	v_pk_mul_f32 v[4:5], v[4:5], v[14:15]
	v_cvt_pk_bf16_f32 v10, v10, v11
	v_mul_f32_e32 v11, 0xbfb8aa3b, v26
	v_exp_f32_e32 v16, v11
	v_mul_f32_e32 v11, 0xbfb8aa3b, v27
	v_exp_f32_e32 v17, v11
	s_nop 0
	v_pk_add_f32 v[16:17], v[16:17], 1.0 op_sel_hi:[1,0]
	s_nop 0
	v_div_scale_f32 v11, s[6:7], v17, v17, 1.0
	v_rcp_f32_e32 v20, v11
	s_nop 0
	v_fma_f32 v21, -v11, v20, 1.0
	v_fmac_f32_e32 v20, v21, v20
	v_div_scale_f32 v21, vcc, 1.0, v17, 1.0
	v_mul_f32_e32 v22, v21, v20
	v_fma_f32 v23, -v11, v22, v21
	v_fmac_f32_e32 v22, v23, v20
	v_fma_f32 v11, -v11, v22, v21
	v_div_fmas_f32 v11, v11, v20, v22
	v_div_fixup_f32 v17, v11, v17, 1.0
	v_div_scale_f32 v11, s[6:7], v16, v16, 1.0
	v_rcp_f32_e32 v20, v11
	s_nop 0
	v_fma_f32 v21, -v11, v20, 1.0
	v_fmac_f32_e32 v20, v21, v20
	v_div_scale_f32 v21, vcc, 1.0, v16, 1.0
	v_mul_f32_e32 v22, v21, v20
	v_fma_f32 v23, -v11, v22, v21
	v_fmac_f32_e32 v22, v23, v20
	v_fma_f32 v11, -v11, v22, v21
	v_div_fmas_f32 v11, v11, v20, v22
	v_div_fixup_f32 v16, v11, v16, 1.0
	v_pk_mul_f32 v[12:13], v[16:17], v[12:13]
	s_nop 0
	v_cvt_pk_bf16_f32 v11, v12, v13
	v_mul_f32_e32 v12, 0xbfb8aa3b, v18
	v_exp_f32_e32 v12, v12
	v_exp_f32_e32 v13, v6
	s_nop 0
	v_pk_add_f32 v[6:7], v[12:13], 1.0 op_sel_hi:[1,0]
	s_nop 0
	v_div_scale_f32 v12, s[6:7], v7, v7, 1.0
	v_rcp_f32_e32 v13, v12
	s_nop 0
	v_fma_f32 v16, -v12, v13, 1.0
	v_fmac_f32_e32 v13, v16, v13
	v_div_scale_f32 v16, vcc, 1.0, v7, 1.0
	v_mul_f32_e32 v17, v16, v13
	v_fma_f32 v18, -v12, v17, v16
	v_fmac_f32_e32 v17, v18, v13
	v_fma_f32 v12, -v12, v17, v16
	v_div_fmas_f32 v12, v12, v13, v17
	v_div_fixup_f32 v7, v12, v7, 1.0
	v_div_scale_f32 v12, s[6:7], v6, v6, 1.0
	v_rcp_f32_e32 v13, v12
	s_nop 0
	v_fma_f32 v16, -v12, v13, 1.0
	v_fmac_f32_e32 v13, v16, v13
	v_div_scale_f32 v16, vcc, 1.0, v6, 1.0
	v_mul_f32_e32 v17, v16, v13
	v_fma_f32 v18, -v12, v17, v16
	v_fmac_f32_e32 v17, v18, v13
	v_fma_f32 v12, -v12, v17, v16
	v_div_fmas_f32 v12, v12, v13, v17
	v_div_fixup_f32 v6, v12, v6, 1.0
	v_pk_mul_f32 v[2:3], v[6:7], v[2:3]
	s_nop 0
	v_cvt_pk_bf16_f32 v12, v2, v3
	v_mul_f32_e32 v2, 0xbfb8aa3b, v14
	v_exp_f32_e32 v2, v2
	v_exp_f32_e32 v3, v0
	s_nop 0
	v_pk_add_f32 v[2:3], v[2:3], 1.0 op_sel_hi:[1,0]
	s_nop 0
	v_div_scale_f32 v0, s[6:7], v3, v3, 1.0
	v_rcp_f32_e32 v6, v0
	s_nop 0
	v_fma_f32 v7, -v0, v6, 1.0
	v_fmac_f32_e32 v6, v7, v6
	v_div_scale_f32 v7, vcc, 1.0, v3, 1.0
	v_mul_f32_e32 v8, v7, v6
	v_fma_f32 v9, -v0, v8, v7
	v_fmac_f32_e32 v8, v9, v6
	v_fma_f32 v0, -v0, v8, v7
	v_div_fmas_f32 v0, v0, v6, v8
	v_div_fixup_f32 v3, v0, v3, 1.0
	v_div_scale_f32 v0, s[6:7], v2, v2, 1.0
	v_rcp_f32_e32 v6, v0
	s_nop 0
	v_fma_f32 v7, -v0, v6, 1.0
	v_fmac_f32_e32 v6, v7, v6
	v_div_scale_f32 v7, vcc, 1.0, v2, 1.0
	v_mul_f32_e32 v8, v7, v6
	v_fma_f32 v9, -v0, v8, v7
	v_fmac_f32_e32 v8, v9, v6
	v_fma_f32 v0, -v0, v8, v7
	v_div_fmas_f32 v0, v0, v6, v8
	v_div_fixup_f32 v2, v0, v2, 1.0
	v_pk_mul_f32 v[2:3], v[2:3], v[4:5]
	s_nop 0
	v_cvt_pk_bf16_f32 v13, v2, v3
	global_store_dwordx4 v[42:43], v[10:13], off offset:192
	s_cbranch_scc1 .LBB0_292
